# grid barrier: non-leader workgroups poll the cross-XCD generation word directly (one hop less on release)
# speedup vs baseline: 1.0111x; 1.0065x over previous
; __device__ __forceinline__ unsigned xb_ld(unsigned* p)              { return __hip_atomic_load(p, __ATOMIC_RELAXED, __HIP_MEMORY_SCOPE_AGENT); }
; __device__ __forceinline__ unsigned xb_add(unsigned* p, unsigned v) { return __hip_atomic_fetch_add(p, v, __ATOMIC_RELAXED, __HIP_MEMORY_SCOPE_AGENT); }
; #define XB_SPIN(cond, bar) do { unsigned _sp = 0; while (cond) { __builtin_amdgcn_s_sleep(1); \
;     if ((++_sp & 255u) == 0u) { if (xb_ld(&(bar)[XB_TMO])) break; if (_sp > XB_SPIN_CAP) { atomicAdd(&(bar)[XB_TMO], 1u); break; } } } } while (0)
; __device__ __forceinline__ void xcd_barrier(const XcdBarrier& b) {
;     ...
;         unsigned nloc = b.st[0], nx = b.st[1];
;         if (nloc == 0u) { xcd_barrier_complete(bar, bx_, nloc, nx); b.st[0] = nloc; b.st[1] = nx; }
;         const unsigned old = xb_add(&bar[XB_XSUB(bx_)], 1u);
;         const unsigned gen = old / nloc;
;         if (old + 1u == (gen + 1u) * nloc) {
;             __builtin_amdgcn_fence(__ATOMIC_RELEASE, "agent");
;             asm volatile("s_waitcnt vmcnt(0)" ::: "memory");
;             const unsigned og = xb_add(&bar[XB_TOP], 1u);
;             const unsigned tg = og / nx;
;             if (og + 1u == (tg + 1u) * nx) xb_add(&bar[XB_TOPGEN], 1u);
;             else XB_SPIN(xb_ld(&bar[XB_TOPGEN]) == tg, bar);
;             __builtin_amdgcn_fence(__ATOMIC_ACQUIRE, "agent");
;             xb_add(&bar[XB_XGEN(bx_)], 1u);
;             asm volatile("s_waitcnt vmcnt(0)" ::: "memory");
;         } else {
;             XB_SPIN(xb_ld(&bar[XB_XGEN(bx_)]) == gen, bar);
;             __builtin_amdgcn_fence(__ATOMIC_ACQUIRE, "agent");
;             asm volatile("s_waitcnt vmcnt(0)" ::: "memory");
;         }
.LBB0_250:
	s_or_b64 exec, exec, s[6:7]
	v_cvt_f32_u32_e32 v5, v3
	s_waitcnt vmcnt(0)
	v_readfirstlane_b32 s4, v4
	v_sub_u32_e32 v4, 0, v3
	v_rcp_iflag_f32_e32 v5, v5
	v_add_u32_e32 v6, s4, v2
	v_mul_f32_e32 v5, 0x4f7ffffe, v5
	v_cvt_u32_f32_e32 v5, v5
	v_mul_lo_u32 v2, v4, v5
	v_mul_hi_u32 v2, v5, v2
	v_add_u32_e32 v2, v5, v2
	v_mul_hi_u32 v2, v6, v2
	v_mul_lo_u32 v4, v2, v3
	v_sub_u32_e32 v4, v6, v4
	v_add_u32_e32 v5, 1, v2
	v_cmp_ge_u32_e32 vcc, v4, v3
	s_nop 1
	v_cndmask_b32_e32 v2, v2, v5, vcc
	v_sub_u32_e32 v5, v4, v3
	v_cndmask_b32_e32 v4, v4, v5, vcc
	v_add_u32_e32 v5, 1, v2
	v_cmp_ge_u32_e32 vcc, v4, v3
	v_add_u32_e32 v4, 1, v6
	s_nop 0
	v_cndmask_b32_e32 v2, v2, v5, vcc
	v_mul_lo_u32 v5, v3, v2
	v_add_u32_e32 v3, v5, v3
	v_cmp_ne_u32_e32 vcc, v4, v3
	s_and_saveexec_b64 s[4:5], vcc
	s_xor_b64 s[4:5], exec, s[4:5]
	s_cbranch_execz .LBB0_264
	s_waitcnt lgkmcnt(0)
	v_readlane_b32 s10, v252, 16
	v_readlane_b32 s11, v252, 17
	v_mov_b32_e32 v1, 0
	s_nop 1
	s_add_u32 s10, s10, 0x7500
	s_addc_u32 s11, s11, 0
	global_load_dword v1, v1, s[10:11] sc1
	s_waitcnt vmcnt(0)
	v_cmp_eq_u32_e32 vcc, v1, v2
	s_and_saveexec_b64 s[6:7], vcc
	s_cbranch_execz .LBB0_263
	v_readlane_b32 s12, v252, 2
	v_readlane_b32 s26, v252, 16
	v_readlane_b32 s13, v252, 3
	v_readlane_b32 s22, v252, 12
	v_readlane_b32 s27, v252, 17
	s_add_u32 s8, s26, 0x4200
	v_readlane_b32 s14, v252, 4
	v_readlane_b32 s15, v252, 5
	s_addc_u32 s9, s27, 0
	s_mov_b32 s22, 1
	s_mov_b64 s[12:13], 0
	v_mov_b32_e32 v1, 0
	v_readlane_b32 s16, v252, 6
	v_readlane_b32 s17, v252, 7
	v_readlane_b32 s18, v252, 8
	v_readlane_b32 s19, v252, 9
	v_readlane_b32 s20, v252, 10
	v_readlane_b32 s21, v252, 11
	v_readlane_b32 s23, v252, 13
	v_readlane_b32 s24, v252, 14
	v_readlane_b32 s25, v252, 15
	s_branch .LBB0_254

; __device__ __forceinline__ unsigned xb_ld(unsigned* p)              { return __hip_atomic_load(p, __ATOMIC_RELAXED, __HIP_MEMORY_SCOPE_AGENT); }
; __device__ __forceinline__ unsigned xb_add(unsigned* p, unsigned v) { return __hip_atomic_fetch_add(p, v, __ATOMIC_RELAXED, __HIP_MEMORY_SCOPE_AGENT); }
; #define XB_SPIN(cond, bar) do { unsigned _sp = 0; while (cond) { __builtin_amdgcn_s_sleep(1); \
;     if ((++_sp & 255u) == 0u) { if (xb_ld(&(bar)[XB_TMO])) break; if (_sp > XB_SPIN_CAP) { atomicAdd(&(bar)[XB_TMO], 1u); break; } } } } while (0)
; __device__ __forceinline__ void xcd_barrier(const XcdBarrier& b) {
;     ...
;         unsigned nloc = b.st[0], nx = b.st[1];
;         if (nloc == 0u) { xcd_barrier_complete(bar, bx_, nloc, nx); b.st[0] = nloc; b.st[1] = nx; }
;         const unsigned old = xb_add(&bar[XB_XSUB(bx_)], 1u);
;         const unsigned gen = old / nloc;
;         if (old + 1u == (gen + 1u) * nloc) {
;             __builtin_amdgcn_fence(__ATOMIC_RELEASE, "agent");
;             asm volatile("s_waitcnt vmcnt(0)" ::: "memory");
;             const unsigned og = xb_add(&bar[XB_TOP], 1u);
;             const unsigned tg = og / nx;
;             if (og + 1u == (tg + 1u) * nx) xb_add(&bar[XB_TOPGEN], 1u);
;             else XB_SPIN(xb_ld(&bar[XB_TOPGEN]) == tg, bar);
;             __builtin_amdgcn_fence(__ATOMIC_ACQUIRE, "agent");
;             xb_add(&bar[XB_XGEN(bx_)], 1u);
;             asm volatile("s_waitcnt vmcnt(0)" ::: "memory");
;         } else {
;             XB_SPIN(xb_ld(&bar[XB_XGEN(bx_)]) == gen, bar);
;             __builtin_amdgcn_fence(__ATOMIC_ACQUIRE, "agent");
;             asm volatile("s_waitcnt vmcnt(0)" ::: "memory");
;         }
.LBB0_510:
	s_or_b64 exec, exec, s[6:7]
	v_cvt_f32_u32_e32 v7, v5
	s_waitcnt vmcnt(0)
	v_readfirstlane_b32 s4, v6
	v_sub_u32_e32 v6, 0, v5
	v_rcp_iflag_f32_e32 v7, v7
	v_add_u32_e32 v8, s4, v2
	v_mul_f32_e32 v7, 0x4f7ffffe, v7
	v_cvt_u32_f32_e32 v7, v7
	v_mul_lo_u32 v2, v6, v7
	v_mul_hi_u32 v2, v7, v2
	v_add_u32_e32 v2, v7, v2
	v_mul_hi_u32 v2, v8, v2
	v_mul_lo_u32 v6, v2, v5
	v_sub_u32_e32 v6, v8, v6
	v_add_u32_e32 v7, 1, v2
	v_cmp_ge_u32_e32 vcc, v6, v5
	s_nop 1
	v_cndmask_b32_e32 v2, v2, v7, vcc
	v_sub_u32_e32 v7, v6, v5
	v_cndmask_b32_e32 v6, v6, v7, vcc
	v_add_u32_e32 v7, 1, v2
	v_cmp_ge_u32_e32 vcc, v6, v5
	v_add_u32_e32 v6, 1, v8
	s_nop 0
	v_cndmask_b32_e32 v2, v2, v7, vcc
	v_mul_lo_u32 v7, v5, v2
	v_add_u32_e32 v5, v7, v5
	v_cmp_ne_u32_e32 vcc, v6, v5
	s_and_saveexec_b64 s[4:5], vcc
	s_xor_b64 s[4:5], exec, s[4:5]
	s_cbranch_execz .LBB0_524
	s_waitcnt lgkmcnt(0)
	v_readlane_b32 s8, v252, 16
	v_readlane_b32 s9, v252, 17
	v_mov_b32_e32 v4, 0
	s_nop 1
	s_add_u32 s8, s8, 0x7500
	s_addc_u32 s9, s9, 0
	global_load_dword v4, v4, s[8:9] sc1
	s_waitcnt vmcnt(0)
	v_cmp_eq_u32_e32 vcc, v4, v2
	s_and_saveexec_b64 s[6:7], vcc
	s_cbranch_execz .LBB0_523
	s_mov_b32 s20, 1
	s_mov_b64 s[10:11], 0
	s_branch .LBB0_514
